# context-row mini-GEMM K-loops: all 16 fragment loads of a k-chunk issued up front behind counted waits (was eight dependent round trips per chunk)
# baseline (speedup 1.0000x reference)
; template <int MODE> __device__ __forceinline__ void mini_gemm_ctx(const u16* A, const u16* Bt, int N, int K, u16* Ob, int ldo, int act, const float* gate, LAS unsigned char* L, int vb, int G_, int wave, int lane) {
;     ...
;         const u16* ap = A + (size_t)(r0 + fr) * K + wave * kslice + 8 * fq; const u16* bp = Bt + (size_t)(n0 + fr) * K + wave * kslice + 8 * fq;
; #pragma unroll 1
;         for (int kc = 0; kc < kslice; kc += 64) {
;             mbf16x8 fa[4][2], fb[4][2];
; #pragma unroll
;             for (int s = 0; s < 2; ++s)
; #pragma unroll
;                 for (int q = 0; q < 4; ++q) { fa[q][s] = *(const mbf16x8*)(ap + (size_t)(16 * q) * K + kc + 32 * s); fb[q][s] = *(const mbf16x8*)(bp + (size_t)(16 * q) * K + kc + 32 * s); }
; #pragma unroll
;             for (int s = 0; s < 2; ++s)
; #pragma unroll
;                 for (int mi = 0; mi < 4; ++mi)
; #pragma unroll
;                     for (int ni = 0; ni < 4; ++ni) acc[mi][ni] = __builtin_amdgcn_mfma_f32_16x16x32_bf16(fa[mi][s], fb[ni][s], acc[mi][ni], 0, 0, 0);
;         }
.LBB0_383:
	v_lshl_add_u64 v[120:121], v[80:81], 0, v[66:67]
	v_lshl_add_u64 v[104:105], v[68:69], 0, v[66:67]
	v_lshl_add_u64 v[106:107], v[82:83], 0, v[66:67]
	v_lshl_add_u64 v[108:109], v[76:77], 0, v[66:67]
	v_lshl_add_u64 v[110:111], v[70:71], 0, v[66:67]
	v_add_co_u32_e32 v124, vcc, s2, v104
	v_add_co_u32_e64 v126, s[44:45], s2, v106
	v_add_co_u32_e64 v128, s[46:47], s2, v108
	v_add_co_u32_e64 v130, s[50:51], s2, v110
	v_addc_co_u32_e32 v125, vcc, 0, v105, vcc
	v_addc_co_u32_e64 v127, vcc, 0, v107, s[44:45]
	v_addc_co_u32_e64 v129, vcc, 0, v109, s[46:47]
	v_addc_co_u32_e64 v131, vcc, 0, v111, s[50:51]
	v_lshl_add_u64 v[122:123], v[72:73], 0, v[66:67]
	v_lshl_add_u64 v[132:133], v[74:75], 0, v[66:67]
	v_lshl_add_u64 v[134:135], v[78:79], 0, v[66:67]
	global_load_dwordx4 v[136:139], v[120:121], off offset:-64
	global_load_dwordx4 v[140:143], v[124:125], off
	global_load_dwordx4 v[144:147], v[126:127], off
	global_load_dwordx4 v[148:151], v[128:129], off
	global_load_dwordx4 v[152:155], v[130:131], off
	global_load_dwordx4 v[156:159], v[122:123], off
	global_load_dwordx4 v[160:163], v[132:133], off
	global_load_dwordx4 v[164:167], v[134:135], off
	global_load_dwordx4 v[168:171], v[120:121], off
	global_load_dwordx4 v[172:175], v[124:125], off offset:64
	global_load_dwordx4 v[176:179], v[126:127], off offset:64
	global_load_dwordx4 v[180:183], v[128:129], off offset:64
	global_load_dwordx4 v[184:187], v[130:131], off offset:64
	global_load_dwordx4 v[188:191], v[122:123], off offset:64
	global_load_dwordx4 v[192:195], v[132:133], off offset:64
	global_load_dwordx4 v[196:199], v[134:135], off offset:64
	s_add_i32 s78, s78, 64
	v_lshl_add_u64 v[68:69], v[68:69], 0, s[24:25]
	v_lshl_add_u64 v[70:71], v[70:71], 0, s[24:25]
	v_lshl_add_u64 v[72:73], v[72:73], 0, s[24:25]
	v_lshl_add_u64 v[74:75], v[74:75], 0, s[24:25]
	v_lshl_add_u64 v[76:77], v[76:77], 0, s[24:25]
	v_lshl_add_u64 v[78:79], v[78:79], 0, s[24:25]
	v_lshl_add_u64 v[80:81], v[80:81], 0, s[24:25]
	v_lshl_add_u64 v[82:83], v[82:83], 0, s[24:25]
	s_cmp_ge_u32 s78, s80
	s_waitcnt vmcnt(11)
	v_mfma_f32_16x16x32_bf16 v[2:5], v[136:139], v[140:143], v[2:5]
	v_mfma_f32_16x16x32_bf16 v[6:9], v[136:139], v[144:147], v[6:9]
	v_mfma_f32_16x16x32_bf16 v[10:13], v[136:139], v[148:151], v[10:13]
	v_mfma_f32_16x16x32_bf16 v[14:17], v[136:139], v[152:155], v[14:17]
	s_waitcnt vmcnt(10)
	v_mfma_f32_16x16x32_bf16 v[18:21], v[156:159], v[140:143], v[18:21]
	v_mfma_f32_16x16x32_bf16 v[22:25], v[156:159], v[144:147], v[22:25]
	v_mfma_f32_16x16x32_bf16 v[26:29], v[156:159], v[148:151], v[26:29]
	v_mfma_f32_16x16x32_bf16 v[30:33], v[156:159], v[152:155], v[30:33]
	s_waitcnt vmcnt(9)
	v_mfma_f32_16x16x32_bf16 v[34:37], v[160:163], v[140:143], v[34:37]
	v_mfma_f32_16x16x32_bf16 v[38:41], v[160:163], v[144:147], v[38:41]
	v_mfma_f32_16x16x32_bf16 v[42:45], v[160:163], v[148:151], v[42:45]
	v_mfma_f32_16x16x32_bf16 v[46:49], v[160:163], v[152:155], v[46:49]
	s_waitcnt vmcnt(8)
	v_mfma_f32_16x16x32_bf16 v[50:53], v[164:167], v[140:143], v[50:53]
	v_mfma_f32_16x16x32_bf16 v[54:57], v[164:167], v[144:147], v[54:57]
	v_mfma_f32_16x16x32_bf16 v[62:65], v[164:167], v[148:151], v[62:65]
	v_mfma_f32_16x16x32_bf16 v[58:61], v[164:167], v[152:155], v[58:61]
	s_waitcnt vmcnt(3)
	v_mfma_f32_16x16x32_bf16 v[2:5], v[168:171], v[172:175], v[2:5]
	v_mfma_f32_16x16x32_bf16 v[6:9], v[168:171], v[176:179], v[6:9]
	v_mfma_f32_16x16x32_bf16 v[10:13], v[168:171], v[180:183], v[10:13]
	v_mfma_f32_16x16x32_bf16 v[14:17], v[168:171], v[184:187], v[14:17]
	s_waitcnt vmcnt(2)
	v_mfma_f32_16x16x32_bf16 v[18:21], v[188:191], v[172:175], v[18:21]
	v_mfma_f32_16x16x32_bf16 v[22:25], v[188:191], v[176:179], v[22:25]
	v_mfma_f32_16x16x32_bf16 v[26:29], v[188:191], v[180:183], v[26:29]
	v_mfma_f32_16x16x32_bf16 v[30:33], v[188:191], v[184:187], v[30:33]
	s_waitcnt vmcnt(1)
	v_mfma_f32_16x16x32_bf16 v[34:37], v[192:195], v[172:175], v[34:37]
	v_mfma_f32_16x16x32_bf16 v[38:41], v[192:195], v[176:179], v[38:41]
	v_mfma_f32_16x16x32_bf16 v[42:45], v[192:195], v[180:183], v[42:45]
	v_mfma_f32_16x16x32_bf16 v[46:49], v[192:195], v[184:187], v[46:49]
	s_waitcnt vmcnt(0)
	v_mfma_f32_16x16x32_bf16 v[50:53], v[196:199], v[172:175], v[50:53]
	v_mfma_f32_16x16x32_bf16 v[54:57], v[196:199], v[176:179], v[54:57]
	v_mfma_f32_16x16x32_bf16 v[62:65], v[196:199], v[180:183], v[62:65]
	v_mfma_f32_16x16x32_bf16 v[58:61], v[196:199], v[184:187], v[58:61]
	s_cbranch_scc0 .LBB0_383
; __device__ __forceinline__ unsigned pk2(float lo, float hi) { return pg8::cvt_pk_bf16(lo, hi); }
; template <int MODE> __device__ __forceinline__ void mini_gemm_ctx(const u16* A, const u16* Bt, int N, int K, u16* Ob, int ldo, int act, const float* gate, LAS unsigned char* L, int vb, int G_, int wave, int lane) {
;     ...
;         for (int ti = 0; ti < 16; ++ti) red[(wave * 16 + ti) * 64 + lane] = acc[ti >> 2][ti & 3];
;         __syncthreads();
; #pragma unroll
;         for (int q = 0; q < 2; ++q) { const int ti = 2 * wave + q, mi = ti >> 2, ni = ti & 3;
;             f32x4 s = red[ti * 64 + lane];
; #pragma unroll
;             for (int w = 1; w < 8; ++w) s += red[(w * 16 + ti) * 64 + lane];
;             const int c = n0 + 16 * ni + fr;
;             if (c < N) {
;                 const float gv = (MODE == 1) ? gate[c] : 1.f;
; #pragma unroll
;                 for (int i = 0; i < 4; ++i) { const int r = r0 + 16 * mi + 4 * fq + i; float v = s[i] * gv;
;                     if (act) { v = fmaxf(v, 0.f); v = v * v; } Ob[(size_t)r * ldo + c] = (u16)(pk2(v, 0.f) & 0xffffu); }
	v_add_u32_e32 v0, s81, v85
	ds_write_b128 v0, v[2:5]
	ds_write_b128 v0, v[6:9] offset:1024
	ds_write_b128 v0, v[10:13] offset:2048
	ds_write_b128 v0, v[14:17] offset:3072
	ds_write_b128 v0, v[18:21] offset:4096
	ds_write_b128 v0, v[22:25] offset:5120
	ds_write_b128 v0, v[26:29] offset:6144
	ds_write_b128 v0, v[30:33] offset:7168
	ds_write_b128 v0, v[34:37] offset:8192
	ds_write_b128 v0, v[38:41] offset:9216
	ds_write_b128 v0, v[42:45] offset:10240
	ds_write_b128 v0, v[46:49] offset:11264
	ds_write_b128 v0, v[50:53] offset:12288
	ds_write_b128 v0, v[54:57] offset:13312
	ds_write_b128 v0, v[62:65] offset:14336
	ds_write_b128 v0, v[58:61] offset:15360
	v_add_u32_e32 v6, s77, v86
	v_or_b32_e32 v2, s85, v87
	v_cmp_gt_i32_e32 vcc, s76, v2
	v_or_b32_e32 v5, 1, v6
	v_or_b32_e32 v4, 2, v6
	v_or_b32_e32 v0, 3, v6
	s_waitcnt lgkmcnt(0)
	s_barrier
	s_and_saveexec_b64 s[44:45], vcc
	s_cbranch_execz .LBB0_386
	v_ashrrev_i32_e32 v3, 31, v2
	v_lshl_add_u64 v[8:9], v[2:3], 2, s[36:37]
	global_load_dword v7, v[8:9], off
	ds_read_b128 v[8:11], v88
	ds_read_b128 v[12:15], v88 offset:16384
	ds_read_b128 v[16:19], v88 offset:32768
	ds_read_b128 v[20:23], v88 offset:49152
	ds_read_b128 v[24:27], v89
	ds_read_b128 v[28:31], v90
	ds_read_b128 v[32:35], v91
	ds_read_b128 v[36:39], v92
	s_waitcnt lgkmcnt(6)
	v_pk_add_f32 v[8:9], v[8:9], v[12:13]
	v_pk_add_f32 v[10:11], v[10:11], v[14:15]
	s_waitcnt lgkmcnt(5)
	v_pk_add_f32 v[8:9], v[8:9], v[16:17]
	v_pk_add_f32 v[10:11], v[10:11], v[18:19]
	s_waitcnt lgkmcnt(4)
	v_pk_add_f32 v[8:9], v[8:9], v[20:21]
	v_pk_add_f32 v[10:11], v[10:11], v[22:23]
	s_waitcnt lgkmcnt(3)
	v_pk_add_f32 v[8:9], v[8:9], v[24:25]
	v_pk_add_f32 v[10:11], v[10:11], v[26:27]
	s_waitcnt lgkmcnt(2)
	v_pk_add_f32 v[8:9], v[8:9], v[28:29]
	v_pk_add_f32 v[10:11], v[10:11], v[30:31]
	s_waitcnt lgkmcnt(1)
	v_pk_add_f32 v[8:9], v[8:9], v[32:33]
	v_mad_i64_i32 v[40:41], s[46:47], v6, s76, 0
	s_waitcnt lgkmcnt(0)
	v_pk_add_f32 v[8:9], v[8:9], v[36:37]
	v_lshl_add_u64 v[2:3], v[2:3], 1, s[18:19]
	v_pk_add_f32 v[10:11], v[10:11], v[34:35]
	v_mad_i64_i32 v[42:43], s[46:47], v5, s76, 0
	v_mad_i64_i32 v[44:45], s[46:47], v4, s76, 0
	v_mad_i64_i32 v[46:47], s[46:47], v0, s76, 0
	v_lshl_add_u64 v[40:41], v[40:41], 1, v[2:3]
	v_pk_add_f32 v[10:11], v[10:11], v[38:39]
	v_lshl_add_u64 v[42:43], v[42:43], 1, v[2:3]
	v_lshl_add_u64 v[44:45], v[44:45], 1, v[2:3]
	v_lshl_add_u64 v[2:3], v[46:47], 1, v[2:3]
	s_waitcnt vmcnt(0)
	v_mul_f32_e32 v8, v7, v8
	v_cvt_pk_bf16_f32 v8, v8, v1
	v_mul_f32_e32 v9, v7, v9
	v_mul_f32_e32 v10, v7, v10
	v_mul_f32_e32 v7, v7, v11
	global_store_short v[40:41], v8, off
	v_cvt_pk_bf16_f32 v8, v9, v1
	global_store_short v[42:43], v8, off
	v_cvt_pk_bf16_f32 v8, v10, v1
	global_store_short v[44:45], v8, off
	v_cvt_pk_bf16_f32 v7, v7, v1
	global_store_short v[2:3], v7, off

; template <int MODE> __device__ __forceinline__ void mini_gemm_ctx(const u16* A, const u16* Bt, int N, int K, u16* Ob, int ldo, int act, const float* gate, LAS unsigned char* L, int vb, int G_, int wave, int lane) {
;     ...
;         const u16* ap = A + (size_t)(r0 + fr) * K + wave * kslice + 8 * fq; const u16* bp = Bt + (size_t)(n0 + fr) * K + wave * kslice + 8 * fq;
; #pragma unroll 1
;         for (int kc = 0; kc < kslice; kc += 64) {
;             mbf16x8 fa[4][2], fb[4][2];
; #pragma unroll
;             for (int s = 0; s < 2; ++s)
; #pragma unroll
;                 for (int q = 0; q < 4; ++q) { fa[q][s] = *(const mbf16x8*)(ap + (size_t)(16 * q) * K + kc + 32 * s); fb[q][s] = *(const mbf16x8*)(bp + (size_t)(16 * q) * K + kc + 32 * s); }
; #pragma unroll
;             for (int s = 0; s < 2; ++s)
; #pragma unroll
;                 for (int mi = 0; mi < 4; ++mi)
; #pragma unroll
;                     for (int ni = 0; ni < 4; ++ni) acc[mi][ni] = __builtin_amdgcn_mfma_f32_16x16x32_bf16(fa[mi][s], fb[ni][s], acc[mi][ni], 0, 0, 0);
;         }
.LBB0_394:
	v_lshl_add_u64 v[120:121], v[80:81], 0, v[66:67]
	v_lshl_add_u64 v[104:105], v[68:69], 0, v[66:67]
	v_lshl_add_u64 v[106:107], v[82:83], 0, v[66:67]
	v_lshl_add_u64 v[108:109], v[76:77], 0, v[66:67]
	v_lshl_add_u64 v[110:111], v[70:71], 0, v[66:67]
	v_add_co_u32_e32 v124, vcc, s2, v104
	v_add_co_u32_e64 v126, s[42:43], s2, v106
	v_add_co_u32_e64 v128, s[44:45], s2, v108
	v_add_co_u32_e64 v130, s[46:47], s2, v110
	v_addc_co_u32_e32 v125, vcc, 0, v105, vcc
	v_addc_co_u32_e64 v127, vcc, 0, v107, s[42:43]
	v_addc_co_u32_e64 v129, vcc, 0, v109, s[44:45]
	v_addc_co_u32_e64 v131, vcc, 0, v111, s[46:47]
	v_lshl_add_u64 v[122:123], v[72:73], 0, v[66:67]
	v_lshl_add_u64 v[132:133], v[74:75], 0, v[66:67]
	v_lshl_add_u64 v[134:135], v[78:79], 0, v[66:67]
	global_load_dwordx4 v[136:139], v[120:121], off offset:-64
	global_load_dwordx4 v[140:143], v[124:125], off
	global_load_dwordx4 v[144:147], v[126:127], off
	global_load_dwordx4 v[148:151], v[128:129], off
	global_load_dwordx4 v[152:155], v[130:131], off
	global_load_dwordx4 v[156:159], v[122:123], off
	global_load_dwordx4 v[160:163], v[132:133], off
	global_load_dwordx4 v[164:167], v[134:135], off
	global_load_dwordx4 v[168:171], v[120:121], off
	global_load_dwordx4 v[172:175], v[124:125], off offset:64
	global_load_dwordx4 v[176:179], v[126:127], off offset:64
	global_load_dwordx4 v[180:183], v[128:129], off offset:64
	global_load_dwordx4 v[184:187], v[130:131], off offset:64
	global_load_dwordx4 v[188:191], v[122:123], off offset:64
	global_load_dwordx4 v[192:195], v[132:133], off offset:64
	global_load_dwordx4 v[196:199], v[134:135], off offset:64
	s_add_i32 s73, s73, 64
	v_lshl_add_u64 v[68:69], v[68:69], 0, s[24:25]
	v_lshl_add_u64 v[70:71], v[70:71], 0, s[24:25]
	v_lshl_add_u64 v[72:73], v[72:73], 0, s[24:25]
	v_lshl_add_u64 v[74:75], v[74:75], 0, s[24:25]
	v_lshl_add_u64 v[76:77], v[76:77], 0, s[24:25]
	v_lshl_add_u64 v[78:79], v[78:79], 0, s[24:25]
	v_lshl_add_u64 v[80:81], v[80:81], 0, s[24:25]
	v_lshl_add_u64 v[82:83], v[82:83], 0, s[24:25]
	s_cmp_ge_u32 s73, s80
	s_waitcnt vmcnt(11)
	v_mfma_f32_16x16x32_bf16 v[2:5], v[136:139], v[140:143], v[2:5]
	v_mfma_f32_16x16x32_bf16 v[6:9], v[136:139], v[144:147], v[6:9]
	v_mfma_f32_16x16x32_bf16 v[10:13], v[136:139], v[148:151], v[10:13]
	v_mfma_f32_16x16x32_bf16 v[14:17], v[136:139], v[152:155], v[14:17]
	s_waitcnt vmcnt(10)
	v_mfma_f32_16x16x32_bf16 v[18:21], v[156:159], v[140:143], v[18:21]
	v_mfma_f32_16x16x32_bf16 v[22:25], v[156:159], v[144:147], v[22:25]
	v_mfma_f32_16x16x32_bf16 v[26:29], v[156:159], v[148:151], v[26:29]
	v_mfma_f32_16x16x32_bf16 v[30:33], v[156:159], v[152:155], v[30:33]
	s_waitcnt vmcnt(9)
	v_mfma_f32_16x16x32_bf16 v[34:37], v[160:163], v[140:143], v[34:37]
	v_mfma_f32_16x16x32_bf16 v[38:41], v[160:163], v[144:147], v[38:41]
	v_mfma_f32_16x16x32_bf16 v[42:45], v[160:163], v[148:151], v[42:45]
	v_mfma_f32_16x16x32_bf16 v[46:49], v[160:163], v[152:155], v[46:49]
	s_waitcnt vmcnt(8)
	v_mfma_f32_16x16x32_bf16 v[50:53], v[164:167], v[140:143], v[50:53]
	v_mfma_f32_16x16x32_bf16 v[54:57], v[164:167], v[144:147], v[54:57]
	v_mfma_f32_16x16x32_bf16 v[62:65], v[164:167], v[148:151], v[62:65]
	v_mfma_f32_16x16x32_bf16 v[58:61], v[164:167], v[152:155], v[58:61]
	s_waitcnt vmcnt(3)
	v_mfma_f32_16x16x32_bf16 v[2:5], v[168:171], v[172:175], v[2:5]
	v_mfma_f32_16x16x32_bf16 v[6:9], v[168:171], v[176:179], v[6:9]
	v_mfma_f32_16x16x32_bf16 v[10:13], v[168:171], v[180:183], v[10:13]
	v_mfma_f32_16x16x32_bf16 v[14:17], v[168:171], v[184:187], v[14:17]
	s_waitcnt vmcnt(2)
	v_mfma_f32_16x16x32_bf16 v[18:21], v[188:191], v[172:175], v[18:21]
	v_mfma_f32_16x16x32_bf16 v[22:25], v[188:191], v[176:179], v[22:25]
	v_mfma_f32_16x16x32_bf16 v[26:29], v[188:191], v[180:183], v[26:29]
	v_mfma_f32_16x16x32_bf16 v[30:33], v[188:191], v[184:187], v[30:33]
	s_waitcnt vmcnt(1)
	v_mfma_f32_16x16x32_bf16 v[34:37], v[192:195], v[172:175], v[34:37]
	v_mfma_f32_16x16x32_bf16 v[38:41], v[192:195], v[176:179], v[38:41]
	v_mfma_f32_16x16x32_bf16 v[42:45], v[192:195], v[180:183], v[42:45]
	v_mfma_f32_16x16x32_bf16 v[46:49], v[192:195], v[184:187], v[46:49]
	s_waitcnt vmcnt(0)
	v_mfma_f32_16x16x32_bf16 v[50:53], v[196:199], v[172:175], v[50:53]
	v_mfma_f32_16x16x32_bf16 v[54:57], v[196:199], v[176:179], v[54:57]
	v_mfma_f32_16x16x32_bf16 v[62:65], v[196:199], v[180:183], v[62:65]
	v_mfma_f32_16x16x32_bf16 v[58:61], v[196:199], v[184:187], v[58:61]
	s_cbranch_scc0 .LBB0_394
; __device__ __forceinline__ unsigned pk2(float lo, float hi) { return pg8::cvt_pk_bf16(lo, hi); }
; template <int MODE> __device__ __forceinline__ void mini_gemm_ctx(const u16* A, const u16* Bt, int N, int K, u16* Ob, int ldo, int act, const float* gate, LAS unsigned char* L, int vb, int G_, int wave, int lane) {
;     ...
;         for (int ti = 0; ti < 16; ++ti) red[(wave * 16 + ti) * 64 + lane] = acc[ti >> 2][ti & 3];
;         __syncthreads();
; #pragma unroll
;         for (int q = 0; q < 2; ++q) { const int ti = 2 * wave + q, mi = ti >> 2, ni = ti & 3;
;             f32x4 s = red[ti * 64 + lane];
; #pragma unroll
;             for (int w = 1; w < 8; ++w) s += red[(w * 16 + ti) * 64 + lane];
;             const int c = n0 + 16 * ni + fr;
;             if (c < N) {
;                 const float gv = (MODE == 1) ? gate[c] : 1.f;
; #pragma unroll
;                 for (int i = 0; i < 4; ++i) { const int r = r0 + 16 * mi + 4 * fq + i; float v = s[i] * gv;
;                     if (act) { v = fmaxf(v, 0.f); v = v * v; } Ob[(size_t)r * ldo + c] = (u16)(pk2(v, 0.f) & 0xffffu); }
	v_add_u32_e32 v0, s81, v85
	ds_write_b128 v0, v[2:5]
	ds_write_b128 v0, v[6:9] offset:1024
	ds_write_b128 v0, v[10:13] offset:2048
	ds_write_b128 v0, v[14:17] offset:3072
	ds_write_b128 v0, v[18:21] offset:4096
	ds_write_b128 v0, v[22:25] offset:5120
	ds_write_b128 v0, v[26:29] offset:6144
	ds_write_b128 v0, v[30:33] offset:7168
	ds_write_b128 v0, v[34:37] offset:8192
	ds_write_b128 v0, v[38:41] offset:9216
	ds_write_b128 v0, v[42:45] offset:10240
	ds_write_b128 v0, v[46:49] offset:11264
	ds_write_b128 v0, v[50:53] offset:12288
	ds_write_b128 v0, v[54:57] offset:13312
	ds_write_b128 v0, v[62:65] offset:14336
	ds_write_b128 v0, v[58:61] offset:15360
	v_add_u32_e32 v6, s72, v86
	v_or_b32_e32 v2, s63, v87
	v_cmp_gt_i32_e32 vcc, s76, v2
	v_or_b32_e32 v5, 1, v6
	v_or_b32_e32 v4, 2, v6
	v_or_b32_e32 v0, 3, v6
	s_waitcnt lgkmcnt(0)
	s_barrier
	s_and_saveexec_b64 s[42:43], vcc
	s_cbranch_execz .LBB0_397
	ds_read_b128 v[8:11], v88
	ds_read_b128 v[12:15], v88 offset:16384
	ds_read_b128 v[16:19], v88 offset:32768
	ds_read_b128 v[20:23], v88 offset:49152
	v_ashrrev_i32_e32 v3, 31, v2
	v_lshl_add_u64 v[2:3], v[2:3], 1, s[18:19]
	s_waitcnt lgkmcnt(2)
	v_pk_add_f32 v[10:11], v[10:11], v[14:15]
	v_pk_add_f32 v[12:13], v[8:9], v[12:13]
	s_waitcnt lgkmcnt(1)
	v_pk_add_f32 v[14:15], v[10:11], v[18:19]
	ds_read_b128 v[8:11], v89
	v_pk_add_f32 v[12:13], v[12:13], v[16:17]
	s_waitcnt lgkmcnt(1)
	v_pk_add_f32 v[16:17], v[14:15], v[22:23]
	v_pk_add_f32 v[20:21], v[12:13], v[20:21]
	ds_read_b128 v[12:15], v90
	s_waitcnt lgkmcnt(1)
	v_pk_add_f32 v[22:23], v[16:17], v[10:11]
	ds_read_b128 v[16:19], v91
	v_pk_add_f32 v[20:21], v[20:21], v[8:9]
	ds_read_b128 v[8:11], v92
	s_waitcnt lgkmcnt(2)
	v_pk_add_f32 v[12:13], v[20:21], v[12:13]
	v_pk_add_f32 v[14:15], v[22:23], v[14:15]
	s_waitcnt lgkmcnt(1)
	v_pk_add_f32 v[12:13], v[12:13], v[16:17]
	v_pk_add_f32 v[14:15], v[14:15], v[18:19]
	s_waitcnt lgkmcnt(0)
	v_pk_add_f32 v[8:9], v[12:13], v[8:9]
	v_mad_i64_i32 v[12:13], s[44:45], v6, s76, 0
	v_max_f32_e32 v7, 0, v8
	v_mul_f32_e32 v7, v7, v7
	v_cndmask_b32_e64 v7, v8, v7, s[38:39]
	v_cvt_pk_bf16_f32 v7, v7, v1
	v_lshl_add_u64 v[12:13], v[12:13], 1, v[2:3]
	global_store_short v[12:13], v7, off
	v_max_f32_e32 v7, 0, v9
	v_mul_f32_e32 v7, v7, v7
	v_cndmask_b32_e64 v7, v9, v7, s[38:39]
	v_mad_i64_i32 v[8:9], s[44:45], v5, s76, 0
	v_pk_add_f32 v[10:11], v[14:15], v[10:11]
	v_cvt_pk_bf16_f32 v7, v7, v1
	v_lshl_add_u64 v[8:9], v[8:9], 1, v[2:3]
	global_store_short v[8:9], v7, off
	v_max_f32_e32 v7, 0, v10
	v_mul_f32_e32 v7, v7, v7
	v_cndmask_b32_e64 v7, v10, v7, s[38:39]
	v_mad_i64_i32 v[8:9], s[44:45], v4, s76, 0
	v_cvt_pk_bf16_f32 v7, v7, v1
	v_lshl_add_u64 v[8:9], v[8:9], 1, v[2:3]
	global_store_short v[8:9], v7, off
	v_max_f32_e32 v7, 0, v11
	v_mul_f32_e32 v7, v7, v7
	v_mad_i64_i32 v[8:9], s[44:45], v0, s76, 0
	v_cndmask_b32_e64 v7, v11, v7, s[38:39]
	v_lshl_add_u64 v[2:3], v[8:9], 1, v[2:3]
	v_cvt_pk_bf16_f32 v7, v7, v1
	global_store_short v[2:3], v7, off
